# RWKV MIX weight conversion: source-selection tree evaluated once per tile, 16 loads behind one wait (both copies) + readout epilogue loads issued ahead
# baseline (speedup 1.0000x reference)
.LBB0_684:
	s_or_b64 exec, exec, s[10:11]
	s_lshl_b32 s10, s63, 6
	v_add_u32_e32 v21, s10, v11
	v_mov_b32_e32 v66, v22
	v_mov_b32_e32 v67, v8
	v_mov_b32_e32 v68, v21
	v_mov_b32_e32 v69, v4
	v_mov_b32_e32 v42, v6
	v_mov_b32_e32 v43, v7
	v_mov_b32_e32 v20, 0
	v_mov_b32_e32 v22, 0
	v_mov_b32_e32 v23, 0
	v_mov_b32_e32 v24, 0
	v_mov_b32_e32 v25, 0
	v_mov_b32_e32 v26, 0
	v_mov_b32_e32 v9, 0
	v_mov_b32_e32 v3, 0
	s_and_saveexec_b64 s[74:75], s[80:81]
	s_cbranch_execz .Lmx_a_skip
	v_and_b32_e32 v40, 0x3f8, v68
	v_mul_u32_u24_e32 v64, v69, v40
	v_lshlrev_b32_e32 v64, 2, v64
	v_mov_b32_e32 v65, v1
	v_lshl_add_u64 v[42:43], v[42:43], 0, v[64:65]
	v_mov_b32_e32 v64, v67
	v_lshl_add_u64 v[42:43], v[64:65], 2, v[42:43]
	v_lshlrev_b32_e32 v44, 2, v69
	v_mov_b32_e32 v45, v1
	v_add_lshl_u32 v41, v66, v40, 2
	global_load_dword v48, v[42:43], off
	global_load_dword v56, v41, s[24:25]
	v_lshl_add_u64 v[42:43], v[42:43], 0, v[44:45]
	global_load_dword v49, v[42:43], off
	global_load_dword v57, v41, s[24:25] offset:4
	v_lshl_add_u64 v[42:43], v[42:43], 0, v[44:45]
	global_load_dword v50, v[42:43], off
	global_load_dword v58, v41, s[24:25] offset:8
	v_lshl_add_u64 v[42:43], v[42:43], 0, v[44:45]
	global_load_dword v51, v[42:43], off
	global_load_dword v59, v41, s[24:25] offset:12
	v_lshl_add_u64 v[42:43], v[42:43], 0, v[44:45]
	global_load_dword v52, v[42:43], off
	global_load_dword v60, v41, s[24:25] offset:16
	v_lshl_add_u64 v[42:43], v[42:43], 0, v[44:45]
	global_load_dword v53, v[42:43], off
	global_load_dword v61, v41, s[24:25] offset:20
	v_lshl_add_u64 v[42:43], v[42:43], 0, v[44:45]
	global_load_dword v54, v[42:43], off
	global_load_dword v62, v41, s[24:25] offset:24
	v_lshl_add_u64 v[42:43], v[42:43], 0, v[44:45]
	global_load_dword v55, v[42:43], off
	global_load_dword v63, v41, s[24:25] offset:28
	s_waitcnt vmcnt(0)
	v_cmp_gt_i32_e32 vcc, s0, v68
	v_sub_f32_e32 v65, 1.0, v56
	v_cndmask_b32_e32 v65, v56, v65, vcc
	v_mul_f32_e32 v20, v48, v65
	v_or_b32_e32 v64, 1, v68
	v_cmp_gt_i32_e32 vcc, s0, v64
	v_sub_f32_e32 v65, 1.0, v57
	v_cndmask_b32_e32 v65, v57, v65, vcc
	v_mul_f32_e32 v22, v49, v65
	v_or_b32_e32 v64, 2, v68
	v_cmp_gt_i32_e32 vcc, s0, v64
	v_sub_f32_e32 v65, 1.0, v58
	v_cndmask_b32_e32 v65, v58, v65, vcc
	v_mul_f32_e32 v23, v50, v65
	v_or_b32_e32 v64, 3, v68
	v_cmp_gt_i32_e32 vcc, s0, v64
	v_sub_f32_e32 v65, 1.0, v59
	v_cndmask_b32_e32 v65, v59, v65, vcc
	v_mul_f32_e32 v24, v51, v65
	v_or_b32_e32 v64, 4, v68
	v_cmp_gt_i32_e32 vcc, s0, v64
	v_sub_f32_e32 v65, 1.0, v60
	v_cndmask_b32_e32 v65, v60, v65, vcc
	v_mul_f32_e32 v25, v52, v65
	v_or_b32_e32 v64, 5, v68
	v_cmp_gt_i32_e32 vcc, s0, v64
	v_sub_f32_e32 v65, 1.0, v61
	v_cndmask_b32_e32 v65, v61, v65, vcc
	v_mul_f32_e32 v26, v53, v65
	v_or_b32_e32 v64, 6, v68
	v_cmp_gt_i32_e32 vcc, s0, v64
	v_sub_f32_e32 v65, 1.0, v62
	v_cndmask_b32_e32 v65, v62, v65, vcc
	v_mul_f32_e32 v9, v54, v65
	v_or_b32_e32 v64, 7, v68
	v_cmp_gt_i32_e32 vcc, s0, v64
	v_sub_f32_e32 v65, 1.0, v63
	v_cndmask_b32_e32 v65, v63, v65, vcc
	v_mul_f32_e32 v3, v55, v65
.Lmx_a_skip:
	s_or_b64 exec, exec, s[74:75]
	s_mov_b64 s[2:3], exec
	s_branch .LBB0_672

.LBB0_974:
	s_or_b64 exec, exec, s[26:27]
	s_lshl_b32 s26, s48, 6
	v_add_u32_e32 v18, s26, v11
	v_mov_b32_e32 v66, v9
	v_mov_b32_e32 v67, v6
	v_mov_b32_e32 v68, v18
	v_mov_b32_e32 v69, v8
	v_mov_b32_e32 v42, v4
	v_mov_b32_e32 v43, v5
	v_mov_b32_e32 v19, 0
	v_mov_b32_e32 v20, 0
	v_mov_b32_e32 v21, 0
	v_mov_b32_e32 v22, 0
	v_mov_b32_e32 v23, 0
	v_mov_b32_e32 v24, 0
	v_mov_b32_e32 v9, 0
	v_mov_b32_e32 v3, 0
	s_and_saveexec_b64 s[46:47], s[8:9]
	s_cbranch_execz .Lmx_b_skip
	v_and_b32_e32 v40, 0x3f8, v68
	v_mul_u32_u24_e32 v64, v69, v40
	v_lshlrev_b32_e32 v64, 2, v64
	v_mov_b32_e32 v65, v1
	v_lshl_add_u64 v[42:43], v[42:43], 0, v[64:65]
	v_mov_b32_e32 v64, v67
	v_lshl_add_u64 v[42:43], v[64:65], 2, v[42:43]
	v_lshlrev_b32_e32 v44, 2, v69
	v_mov_b32_e32 v45, v1
	v_add_lshl_u32 v41, v66, v40, 2
	global_load_dword v48, v[42:43], off
	global_load_dword v56, v41, s[52:53]
	v_lshl_add_u64 v[42:43], v[42:43], 0, v[44:45]
	global_load_dword v49, v[42:43], off
	global_load_dword v57, v41, s[52:53] offset:4
	v_lshl_add_u64 v[42:43], v[42:43], 0, v[44:45]
	global_load_dword v50, v[42:43], off
	global_load_dword v58, v41, s[52:53] offset:8
	v_lshl_add_u64 v[42:43], v[42:43], 0, v[44:45]
	global_load_dword v51, v[42:43], off
	global_load_dword v59, v41, s[52:53] offset:12
	v_lshl_add_u64 v[42:43], v[42:43], 0, v[44:45]
	global_load_dword v52, v[42:43], off
	global_load_dword v60, v41, s[52:53] offset:16
	v_lshl_add_u64 v[42:43], v[42:43], 0, v[44:45]
	global_load_dword v53, v[42:43], off
	global_load_dword v61, v41, s[52:53] offset:20
	v_lshl_add_u64 v[42:43], v[42:43], 0, v[44:45]
	global_load_dword v54, v[42:43], off
	global_load_dword v62, v41, s[52:53] offset:24
	v_lshl_add_u64 v[42:43], v[42:43], 0, v[44:45]
	global_load_dword v55, v[42:43], off
	global_load_dword v63, v41, s[52:53] offset:28
	s_waitcnt vmcnt(0)
	v_cmp_gt_i32_e32 vcc, s68, v68
	v_sub_f32_e32 v65, 1.0, v56
	v_cndmask_b32_e32 v65, v56, v65, vcc
	v_mul_f32_e32 v19, v48, v65
	v_or_b32_e32 v64, 1, v68
	v_cmp_gt_i32_e32 vcc, s68, v64
	v_sub_f32_e32 v65, 1.0, v57
	v_cndmask_b32_e32 v65, v57, v65, vcc
	v_mul_f32_e32 v20, v49, v65
	v_or_b32_e32 v64, 2, v68
	v_cmp_gt_i32_e32 vcc, s68, v64
	v_sub_f32_e32 v65, 1.0, v58
	v_cndmask_b32_e32 v65, v58, v65, vcc
	v_mul_f32_e32 v21, v50, v65
	v_or_b32_e32 v64, 3, v68
	v_cmp_gt_i32_e32 vcc, s68, v64
	v_sub_f32_e32 v65, 1.0, v59
	v_cndmask_b32_e32 v65, v59, v65, vcc
	v_mul_f32_e32 v22, v51, v65
	v_or_b32_e32 v64, 4, v68
	v_cmp_gt_i32_e32 vcc, s68, v64
	v_sub_f32_e32 v65, 1.0, v60
	v_cndmask_b32_e32 v65, v60, v65, vcc
	v_mul_f32_e32 v23, v52, v65
	v_or_b32_e32 v64, 5, v68
	v_cmp_gt_i32_e32 vcc, s68, v64
	v_sub_f32_e32 v65, 1.0, v61
	v_cndmask_b32_e32 v65, v61, v65, vcc
	v_mul_f32_e32 v24, v53, v65
	v_or_b32_e32 v64, 6, v68
	v_cmp_gt_i32_e32 vcc, s68, v64
	v_sub_f32_e32 v65, 1.0, v62
	v_cndmask_b32_e32 v65, v62, v65, vcc
	v_mul_f32_e32 v9, v54, v65
	v_or_b32_e32 v64, 7, v68
	v_cmp_gt_i32_e32 vcc, s68, v64
	v_sub_f32_e32 v65, 1.0, v63
	v_cndmask_b32_e32 v65, v63, v65, vcc
	v_mul_f32_e32 v3, v55, v65
.Lmx_b_skip:
	s_or_b64 exec, exec, s[46:47]
	s_mov_b64 s[8:9], exec
	s_branch .LBB0_967
